# grid barrier: leader L2 invalidate issued with its write-back (complete before the cross-XCD arrival); other workgroups wait on the cross-XCD generation word directly
# baseline (speedup 1.0000x reference)
; __device__ __forceinline__ unsigned xb_ld(unsigned* p)              { return __hip_atomic_load(p, __ATOMIC_RELAXED, __HIP_MEMORY_SCOPE_AGENT); }
; __device__ __forceinline__ unsigned xb_add(unsigned* p, unsigned v) { return __hip_atomic_fetch_add(p, v, __ATOMIC_RELAXED, __HIP_MEMORY_SCOPE_AGENT); }
; #define XB_SPIN(cond, bar) do { unsigned _sp = 0; while (cond) { __builtin_amdgcn_s_sleep(1); \
;     if ((++_sp & 255u) == 0u) { if (xb_ld(&(bar)[XB_TMO])) break; if (_sp > XB_SPIN_CAP) { atomicAdd(&(bar)[XB_TMO], 1u); break; } } } } while (0)
; __device__ __forceinline__ void xcd_barrier(const XcdBarrier& b) {
;     ...
;     if (threadIdx.x == 0) {
;         unsigned* bar = b.bar;
;         __builtin_amdgcn_s_waitcnt(0);
;         unsigned nloc = b.st[0], nx = b.st[1];
;         if (nloc == 0u) { xcd_barrier_complete(bar, b.x, nloc, nx); b.st[0] = nloc; b.st[1] = nx; }
;         const unsigned old = xb_add(&bar[XB_XSUB(b.x)], 1u);
;         const unsigned gen = old / nloc;
;         if (old + 1u == (gen + 1u) * nloc) {
;             __builtin_amdgcn_fence(__ATOMIC_RELEASE, "agent");
;             asm volatile("s_waitcnt vmcnt(0)" ::: "memory");
;             const unsigned og = xb_add(&bar[XB_TOP], 1u);
;             const unsigned tg = og / nx;
;             if (og + 1u == (tg + 1u) * nx) xb_add(&bar[XB_TOPGEN], 1u);
;             else XB_SPIN(xb_ld(&bar[XB_TOPGEN]) == tg, bar);
;             __builtin_amdgcn_fence(__ATOMIC_ACQUIRE, "agent");
;             xb_add(&bar[XB_XGEN(b.x)], 1u);
;             asm volatile("s_waitcnt vmcnt(0)" ::: "memory");
;         } else {
;             XB_SPIN(xb_ld(&bar[XB_XGEN(b.x)]) == gen, bar);
.LBB0_279:
	v_readlane_b32 s0, v255, 4
	s_lshl_b32 s22, s33, 6
	v_readlane_b32 s1, v255, 5
	s_mov_b32 s5, s1
	s_add_i32 s4, s22, 0x500
	v_writelane_b32 v255, s0, 4
	v_mov_b32_e32 v1, 1
	s_nop 0
	v_writelane_b32 v255, s1, 5
	s_lshl_b64 s[0:1], s[4:5], 2
	s_add_u32 s0, s34, s0
	s_addc_u32 s1, s35, s1
	v_mov_b64_e32 v[4:5], s[0:1]
	flat_atomic_add v3, v[4:5], v1 sc0
	v_cvt_f32_u32_e32 v1, v2
	v_sub_u32_e32 v4, 0, v2
	v_rcp_iflag_f32_e32 v1, v1
	s_nop 0
	v_mul_f32_e32 v1, 0x4f7ffffe, v1
	v_cvt_u32_f32_e32 v1, v1
	v_mul_lo_u32 v4, v4, v1
	v_mul_hi_u32 v4, v1, v4
	v_add_u32_e32 v1, v1, v4
	s_waitcnt vmcnt(0) lgkmcnt(0)
	v_mul_hi_u32 v1, v3, v1
	v_mul_lo_u32 v4, v1, v2
	v_sub_u32_e32 v4, v3, v4
	v_cmp_ge_u32_e32 vcc, v4, v2
	v_add_u32_e32 v5, 1, v1
	s_nop 0
	v_cndmask_b32_e32 v1, v1, v5, vcc
	v_sub_u32_e32 v5, v4, v2
	v_cndmask_b32_e32 v4, v4, v5, vcc
	v_cmp_ge_u32_e32 vcc, v4, v2
	v_add_u32_e32 v4, 1, v1
	s_nop 0
	v_cndmask_b32_e32 v1, v1, v4, vcc
	v_add_u32_e32 v4, 1, v3
	v_mad_u64_u32 v[2:3], s[0:1], v2, v1, v[2:3]
	v_cmp_ne_u32_e32 vcc, v4, v2
	s_and_saveexec_b64 s[0:1], vcc
	s_xor_b64 s[0:1], exec, s[0:1]
	s_cbranch_execz .LBB0_292
	buffer_inv sc1
	v_readlane_b32 s4, v255, 4
	v_readlane_b32 s5, v255, 5
	s_mov_b32 s7, s5
	s_movk_i32 s6, 0xd40
	v_writelane_b32 v255, s4, 4
	s_nop 1
	v_writelane_b32 v255, s5, 5
	s_lshl_b64 s[4:5], s[6:7], 2
	s_add_u32 s6, s34, s4
	s_addc_u32 s7, s35, s5
	v_mov_b64_e32 v[2:3], s[6:7]
	flat_load_dword v0, v[2:3] sc1
	s_waitcnt vmcnt(0) lgkmcnt(0)
	v_cmp_eq_u32_e32 vcc, v0, v1
	s_and_saveexec_b64 s[4:5], vcc
	s_cbranch_execz .LBB0_291
	s_mov_b32 s23, 1
	s_mov_b64 s[8:9], 0
	s_branch .LBB0_283

; __device__ __forceinline__ unsigned xb_ld(unsigned* p)              { return __hip_atomic_load(p, __ATOMIC_RELAXED, __HIP_MEMORY_SCOPE_AGENT); }
; __device__ __forceinline__ unsigned xb_add(unsigned* p, unsigned v) { return __hip_atomic_fetch_add(p, v, __ATOMIC_RELAXED, __HIP_MEMORY_SCOPE_AGENT); }
; #define XB_SPIN(cond, bar) do { unsigned _sp = 0; while (cond) { __builtin_amdgcn_s_sleep(1); \
;     if ((++_sp & 255u) == 0u) { if (xb_ld(&(bar)[XB_TMO])) break; if (_sp > XB_SPIN_CAP) { atomicAdd(&(bar)[XB_TMO], 1u); break; } } } } while (0)
; __device__ __forceinline__ void xcd_barrier(const XcdBarrier& b) {
;     ...
;         if (old + 1u == (gen + 1u) * nloc) {
;             __builtin_amdgcn_fence(__ATOMIC_RELEASE, "agent");
;             asm volatile("s_waitcnt vmcnt(0)" ::: "memory");
;             const unsigned og = xb_add(&bar[XB_TOP], 1u);
;             const unsigned tg = og / nx;
;             if (og + 1u == (tg + 1u) * nx) xb_add(&bar[XB_TOPGEN], 1u);
;             else XB_SPIN(xb_ld(&bar[XB_TOPGEN]) == tg, bar);
.LBB0_292:
	s_andn2_saveexec_b64 s[0:1], s[0:1]
	s_cbranch_execz .LBB0_308
	v_mov_b32_e32 v1, s34
	v_add_co_u32_e32 v2, vcc, 0x3000, v1
	v_mov_b32_e32 v1, s35
	buffer_inv sc1
	buffer_wbl2 sc1
	s_waitcnt vmcnt(0)
	v_addc_co_u32_e32 v3, vcc, 0, v1, vcc
	v_mov_b32_e32 v1, 1
	flat_atomic_add v1, v[2:3], v1 offset:1024 sc0
	v_cvt_f32_u32_e32 v2, v0
	v_sub_u32_e32 v3, 0, v0
	s_mov_b64 s[6:7], -1
	v_rcp_iflag_f32_e32 v2, v2
	s_nop 0
	v_mul_f32_e32 v2, 0x4f7ffffe, v2
	v_cvt_u32_f32_e32 v2, v2
	v_mul_lo_u32 v3, v3, v2
	v_mul_hi_u32 v3, v2, v3
	v_add_u32_e32 v2, v2, v3
	s_waitcnt vmcnt(0) lgkmcnt(0)
	v_mul_hi_u32 v2, v1, v2
	v_mul_lo_u32 v3, v2, v0
	v_sub_u32_e32 v3, v1, v3
	v_cmp_ge_u32_e32 vcc, v3, v0
	v_add_u32_e32 v4, 1, v2
	s_nop 0
	v_cndmask_b32_e32 v2, v2, v4, vcc
	v_sub_u32_e32 v4, v3, v0
	v_cndmask_b32_e32 v3, v3, v4, vcc
	v_cmp_ge_u32_e32 vcc, v3, v0
	v_add_u32_e32 v3, 1, v2
	s_nop 0
	v_cndmask_b32_e32 v2, v2, v3, vcc
	v_add_u32_e32 v3, 1, v1
	v_mad_u64_u32 v[0:1], s[0:1], v0, v2, v[0:1]
	s_add_u32 s0, s34, 0x3500
	s_addc_u32 s1, s35, 0
	v_cmp_ne_u32_e32 vcc, v3, v0
	v_mov_b64_e32 v[0:1], s[0:1]
	s_and_saveexec_b64 s[4:5], vcc
	s_cbranch_execz .LBB0_305
	v_mov_b64_e32 v[0:1], s[0:1]
	flat_load_dword v0, v[0:1] sc1
	s_mov_b64 s[10:11], 0
	s_waitcnt vmcnt(0) lgkmcnt(0)
	v_cmp_eq_u32_e32 vcc, v0, v2
	s_and_saveexec_b64 s[8:9], vcc
	s_cbranch_execz .LBB0_304
	s_add_u32 s6, s34, 0x200
	s_addc_u32 s7, s35, 0
	s_mov_b32 s23, 1
	s_branch .LBB0_297

; __device__ __forceinline__ unsigned xb_ld(unsigned* p)              { return __hip_atomic_load(p, __ATOMIC_RELAXED, __HIP_MEMORY_SCOPE_AGENT); }
; __device__ __forceinline__ unsigned xb_add(unsigned* p, unsigned v) { return __hip_atomic_fetch_add(p, v, __ATOMIC_RELAXED, __HIP_MEMORY_SCOPE_AGENT); }
; #define XB_SPIN(cond, bar) do { unsigned _sp = 0; while (cond) { __builtin_amdgcn_s_sleep(1); \
;     if ((++_sp & 255u) == 0u) { if (xb_ld(&(bar)[XB_TMO])) break; if (_sp > XB_SPIN_CAP) { atomicAdd(&(bar)[XB_TMO], 1u); break; } } } } while (0)
; __device__ __forceinline__ void xcd_barrier(const XcdBarrier& b) {
;     ...
;     if (threadIdx.x == 0) {
;         unsigned* bar = b.bar;
;         __builtin_amdgcn_s_waitcnt(0);
;         unsigned nloc = b.st[0], nx = b.st[1];
;         if (nloc == 0u) { xcd_barrier_complete(bar, b.x, nloc, nx); b.st[0] = nloc; b.st[1] = nx; }
;         const unsigned old = xb_add(&bar[XB_XSUB(b.x)], 1u);
;         const unsigned gen = old / nloc;
;         if (old + 1u == (gen + 1u) * nloc) {
;             __builtin_amdgcn_fence(__ATOMIC_RELEASE, "agent");
;             asm volatile("s_waitcnt vmcnt(0)" ::: "memory");
;             const unsigned og = xb_add(&bar[XB_TOP], 1u);
;             const unsigned tg = og / nx;
;             if (og + 1u == (tg + 1u) * nx) xb_add(&bar[XB_TOPGEN], 1u);
;             else XB_SPIN(xb_ld(&bar[XB_TOPGEN]) == tg, bar);
;             __builtin_amdgcn_fence(__ATOMIC_ACQUIRE, "agent");
;             xb_add(&bar[XB_XGEN(b.x)], 1u);
;             asm volatile("s_waitcnt vmcnt(0)" ::: "memory");
;         } else {
;             XB_SPIN(xb_ld(&bar[XB_XGEN(b.x)]) == gen, bar);
.LBB0_669:
	v_readlane_b32 s0, v255, 4
	s_lshl_b32 s20, s33, 6
	v_readlane_b32 s1, v255, 5
	s_mov_b32 s3, s1
	s_add_i32 s2, s20, 0x500
	v_writelane_b32 v255, s0, 4
	v_mov_b32_e32 v1, 1
	s_nop 0
	v_writelane_b32 v255, s1, 5
	s_lshl_b64 s[0:1], s[2:3], 2
	s_add_u32 s0, s34, s0
	s_addc_u32 s1, s35, s1
	v_mov_b64_e32 v[4:5], s[0:1]
	flat_atomic_add v3, v[4:5], v1 sc0
	v_cvt_f32_u32_e32 v1, v2
	v_sub_u32_e32 v4, 0, v2
	v_rcp_iflag_f32_e32 v1, v1
	s_nop 0
	v_mul_f32_e32 v1, 0x4f7ffffe, v1
	v_cvt_u32_f32_e32 v1, v1
	v_mul_lo_u32 v4, v4, v1
	v_mul_hi_u32 v4, v1, v4
	v_add_u32_e32 v1, v1, v4
	s_waitcnt vmcnt(0) lgkmcnt(0)
	v_mul_hi_u32 v1, v3, v1
	v_mul_lo_u32 v4, v1, v2
	v_sub_u32_e32 v4, v3, v4
	v_cmp_ge_u32_e32 vcc, v4, v2
	v_add_u32_e32 v5, 1, v1
	s_nop 0
	v_cndmask_b32_e32 v1, v1, v5, vcc
	v_sub_u32_e32 v5, v4, v2
	v_cndmask_b32_e32 v4, v4, v5, vcc
	v_cmp_ge_u32_e32 vcc, v4, v2
	v_add_u32_e32 v4, 1, v1
	s_nop 0
	v_cndmask_b32_e32 v1, v1, v4, vcc
	v_add_u32_e32 v4, 1, v3
	v_mad_u64_u32 v[2:3], s[0:1], v2, v1, v[2:3]
	v_cmp_ne_u32_e32 vcc, v4, v2
	s_and_saveexec_b64 s[0:1], vcc
	s_xor_b64 s[0:1], exec, s[0:1]
	s_cbranch_execz .LBB0_682
	buffer_inv sc1
	v_readlane_b32 s2, v255, 4
	v_readlane_b32 s3, v255, 5
	s_mov_b32 s5, s3
	s_movk_i32 s4, 0xd40
	v_writelane_b32 v255, s2, 4
	s_nop 1
	v_writelane_b32 v255, s3, 5
	s_lshl_b64 s[2:3], s[4:5], 2
	s_add_u32 s4, s34, s2
	s_addc_u32 s5, s35, s3
	v_mov_b64_e32 v[2:3], s[4:5]
	flat_load_dword v0, v[2:3] sc1
	s_waitcnt vmcnt(0) lgkmcnt(0)
	v_cmp_eq_u32_e32 vcc, v0, v1
	s_and_saveexec_b64 s[2:3], vcc
	s_cbranch_execz .LBB0_681
	s_mov_b32 s21, 1
	s_mov_b64 s[6:7], 0
	s_branch .LBB0_673

; __device__ __forceinline__ unsigned xb_ld(unsigned* p)              { return __hip_atomic_load(p, __ATOMIC_RELAXED, __HIP_MEMORY_SCOPE_AGENT); }
; __device__ __forceinline__ unsigned xb_add(unsigned* p, unsigned v) { return __hip_atomic_fetch_add(p, v, __ATOMIC_RELAXED, __HIP_MEMORY_SCOPE_AGENT); }
; #define XB_SPIN(cond, bar) do { unsigned _sp = 0; while (cond) { __builtin_amdgcn_s_sleep(1); \
;     if ((++_sp & 255u) == 0u) { if (xb_ld(&(bar)[XB_TMO])) break; if (_sp > XB_SPIN_CAP) { atomicAdd(&(bar)[XB_TMO], 1u); break; } } } } while (0)
; __device__ __forceinline__ void xcd_barrier(const XcdBarrier& b) {
;     ...
;         if (old + 1u == (gen + 1u) * nloc) {
;             __builtin_amdgcn_fence(__ATOMIC_RELEASE, "agent");
;             asm volatile("s_waitcnt vmcnt(0)" ::: "memory");
;             const unsigned og = xb_add(&bar[XB_TOP], 1u);
;             const unsigned tg = og / nx;
;             if (og + 1u == (tg + 1u) * nx) xb_add(&bar[XB_TOPGEN], 1u);
;             else XB_SPIN(xb_ld(&bar[XB_TOPGEN]) == tg, bar);
.LBB0_682:
	s_andn2_saveexec_b64 s[0:1], s[0:1]
	s_cbranch_execz .LBB0_698
	v_mov_b32_e32 v1, s34
	v_add_co_u32_e32 v2, vcc, 0x3000, v1
	v_mov_b32_e32 v1, s35
	buffer_inv sc1
	buffer_wbl2 sc1
	s_waitcnt vmcnt(0)
	v_addc_co_u32_e32 v3, vcc, 0, v1, vcc
	v_mov_b32_e32 v1, 1
	flat_atomic_add v1, v[2:3], v1 offset:1024 sc0
	v_cvt_f32_u32_e32 v2, v0
	v_sub_u32_e32 v3, 0, v0
	s_mov_b64 s[4:5], -1
	v_rcp_iflag_f32_e32 v2, v2
	s_nop 0
	v_mul_f32_e32 v2, 0x4f7ffffe, v2
	v_cvt_u32_f32_e32 v2, v2
	v_mul_lo_u32 v3, v3, v2
	v_mul_hi_u32 v3, v2, v3
	v_add_u32_e32 v2, v2, v3
	s_waitcnt vmcnt(0) lgkmcnt(0)
	v_mul_hi_u32 v2, v1, v2
	v_mul_lo_u32 v3, v2, v0
	v_sub_u32_e32 v3, v1, v3
	v_cmp_ge_u32_e32 vcc, v3, v0
	v_add_u32_e32 v4, 1, v2
	s_nop 0
	v_cndmask_b32_e32 v2, v2, v4, vcc
	v_sub_u32_e32 v4, v3, v0
	v_cndmask_b32_e32 v3, v3, v4, vcc
	v_cmp_ge_u32_e32 vcc, v3, v0
	v_add_u32_e32 v3, 1, v2
	s_nop 0
	v_cndmask_b32_e32 v2, v2, v3, vcc
	v_add_u32_e32 v3, 1, v1
	v_mad_u64_u32 v[0:1], s[0:1], v0, v2, v[0:1]
	s_add_u32 s0, s34, 0x3500
	s_addc_u32 s1, s35, 0
	v_cmp_ne_u32_e32 vcc, v3, v0
	v_mov_b64_e32 v[0:1], s[0:1]
	s_and_saveexec_b64 s[2:3], vcc
	s_cbranch_execz .LBB0_695
	v_mov_b64_e32 v[0:1], s[0:1]
	flat_load_dword v0, v[0:1] sc1
	s_mov_b64 s[8:9], 0
	s_waitcnt vmcnt(0) lgkmcnt(0)
	v_cmp_eq_u32_e32 vcc, v0, v2
	s_and_saveexec_b64 s[6:7], vcc
	s_cbranch_execz .LBB0_694
	s_add_u32 s4, s34, 0x200
	s_addc_u32 s5, s35, 0
	s_mov_b32 s21, 1
	s_branch .LBB0_687

; __device__ __forceinline__ unsigned xb_ld(unsigned* p)              { return __hip_atomic_load(p, __ATOMIC_RELAXED, __HIP_MEMORY_SCOPE_AGENT); }
; __device__ __forceinline__ unsigned xb_add(unsigned* p, unsigned v) { return __hip_atomic_fetch_add(p, v, __ATOMIC_RELAXED, __HIP_MEMORY_SCOPE_AGENT); }
; #define XB_SPIN(cond, bar) do { unsigned _sp = 0; while (cond) { __builtin_amdgcn_s_sleep(1); \
;     if ((++_sp & 255u) == 0u) { if (xb_ld(&(bar)[XB_TMO])) break; if (_sp > XB_SPIN_CAP) { atomicAdd(&(bar)[XB_TMO], 1u); break; } } } } while (0)
; __device__ __forceinline__ void xcd_barrier(const XcdBarrier& b) {
;     ...
;     if (threadIdx.x == 0) {
;         unsigned* bar = b.bar;
;         __builtin_amdgcn_s_waitcnt(0);
;         unsigned nloc = b.st[0], nx = b.st[1];
;         if (nloc == 0u) { xcd_barrier_complete(bar, b.x, nloc, nx); b.st[0] = nloc; b.st[1] = nx; }
;         const unsigned old = xb_add(&bar[XB_XSUB(b.x)], 1u);
;         const unsigned gen = old / nloc;
;         if (old + 1u == (gen + 1u) * nloc) {
;             __builtin_amdgcn_fence(__ATOMIC_RELEASE, "agent");
;             asm volatile("s_waitcnt vmcnt(0)" ::: "memory");
;             const unsigned og = xb_add(&bar[XB_TOP], 1u);
;             const unsigned tg = og / nx;
;             if (og + 1u == (tg + 1u) * nx) xb_add(&bar[XB_TOPGEN], 1u);
;             else XB_SPIN(xb_ld(&bar[XB_TOPGEN]) == tg, bar);
;             __builtin_amdgcn_fence(__ATOMIC_ACQUIRE, "agent");
;             xb_add(&bar[XB_XGEN(b.x)], 1u);
;             asm volatile("s_waitcnt vmcnt(0)" ::: "memory");
;         } else {
;             XB_SPIN(xb_ld(&bar[XB_XGEN(b.x)]) == gen, bar);
.LBB0_828:
	v_readlane_b32 s0, v255, 4
	s_lshl_b32 s22, s33, 6
	v_readlane_b32 s1, v255, 5
	s_mov_b32 s3, s1
	s_add_i32 s2, s22, 0x500
	v_writelane_b32 v255, s0, 4
	v_mov_b32_e32 v1, 1
	s_nop 0
	v_writelane_b32 v255, s1, 5
	s_lshl_b64 s[0:1], s[2:3], 2
	s_add_u32 s0, s36, s0
	s_addc_u32 s1, s37, s1
	v_mov_b64_e32 v[4:5], s[0:1]
	flat_atomic_add v3, v[4:5], v1 sc0
	v_cvt_f32_u32_e32 v1, v2
	v_sub_u32_e32 v4, 0, v2
	v_rcp_iflag_f32_e32 v1, v1
	s_nop 0
	v_mul_f32_e32 v1, 0x4f7ffffe, v1
	v_cvt_u32_f32_e32 v1, v1
	v_mul_lo_u32 v4, v4, v1
	v_mul_hi_u32 v4, v1, v4
	v_add_u32_e32 v1, v1, v4
	s_waitcnt vmcnt(0) lgkmcnt(0)
	v_mul_hi_u32 v1, v3, v1
	v_mul_lo_u32 v4, v1, v2
	v_sub_u32_e32 v4, v3, v4
	v_cmp_ge_u32_e32 vcc, v4, v2
	v_add_u32_e32 v5, 1, v1
	s_nop 0
	v_cndmask_b32_e32 v1, v1, v5, vcc
	v_sub_u32_e32 v5, v4, v2
	v_cndmask_b32_e32 v4, v4, v5, vcc
	v_cmp_ge_u32_e32 vcc, v4, v2
	v_add_u32_e32 v4, 1, v1
	s_nop 0
	v_cndmask_b32_e32 v1, v1, v4, vcc
	v_add_u32_e32 v4, 1, v3
	v_mad_u64_u32 v[2:3], s[0:1], v2, v1, v[2:3]
	v_cmp_ne_u32_e32 vcc, v4, v2
	s_and_saveexec_b64 s[0:1], vcc
	s_xor_b64 s[0:1], exec, s[0:1]
	s_cbranch_execz .LBB0_841
	buffer_inv sc1
	v_readlane_b32 s2, v255, 4
	v_readlane_b32 s3, v255, 5
	s_mov_b32 s7, s3
	s_movk_i32 s6, 0xd40
	v_writelane_b32 v255, s2, 4
	s_nop 1
	v_writelane_b32 v255, s3, 5
	s_lshl_b64 s[2:3], s[6:7], 2
	s_add_u32 s6, s36, s2
	s_addc_u32 s7, s37, s3
	v_mov_b64_e32 v[2:3], s[6:7]
	flat_load_dword v0, v[2:3] sc1
	s_waitcnt vmcnt(0) lgkmcnt(0)
	v_cmp_eq_u32_e32 vcc, v0, v1
	s_and_saveexec_b64 s[2:3], vcc
	s_cbranch_execz .LBB0_840
	s_mov_b32 s23, 1
	s_mov_b64 s[8:9], 0
	s_branch .LBB0_832

; __device__ __forceinline__ unsigned xb_ld(unsigned* p)              { return __hip_atomic_load(p, __ATOMIC_RELAXED, __HIP_MEMORY_SCOPE_AGENT); }
; __device__ __forceinline__ unsigned xb_add(unsigned* p, unsigned v) { return __hip_atomic_fetch_add(p, v, __ATOMIC_RELAXED, __HIP_MEMORY_SCOPE_AGENT); }
; #define XB_SPIN(cond, bar) do { unsigned _sp = 0; while (cond) { __builtin_amdgcn_s_sleep(1); \
;     if ((++_sp & 255u) == 0u) { if (xb_ld(&(bar)[XB_TMO])) break; if (_sp > XB_SPIN_CAP) { atomicAdd(&(bar)[XB_TMO], 1u); break; } } } } while (0)
; __device__ __forceinline__ void xcd_barrier(const XcdBarrier& b) {
;     ...
;         if (old + 1u == (gen + 1u) * nloc) {
;             __builtin_amdgcn_fence(__ATOMIC_RELEASE, "agent");
;             asm volatile("s_waitcnt vmcnt(0)" ::: "memory");
;             const unsigned og = xb_add(&bar[XB_TOP], 1u);
;             const unsigned tg = og / nx;
;             if (og + 1u == (tg + 1u) * nx) xb_add(&bar[XB_TOPGEN], 1u);
;             else XB_SPIN(xb_ld(&bar[XB_TOPGEN]) == tg, bar);
.LBB0_841:
	s_andn2_saveexec_b64 s[0:1], s[0:1]
	s_cbranch_execz .LBB0_857
	v_mov_b32_e32 v1, s36
	v_add_co_u32_e32 v2, vcc, 0x3000, v1
	v_mov_b32_e32 v1, s37
	buffer_inv sc1
	buffer_wbl2 sc1
	s_waitcnt vmcnt(0)
	v_addc_co_u32_e32 v3, vcc, 0, v1, vcc
	v_mov_b32_e32 v1, 1
	flat_atomic_add v1, v[2:3], v1 offset:1024 sc0
	v_cvt_f32_u32_e32 v2, v0
	v_sub_u32_e32 v3, 0, v0
	s_mov_b64 s[6:7], -1
	v_rcp_iflag_f32_e32 v2, v2
	s_nop 0
	v_mul_f32_e32 v2, 0x4f7ffffe, v2
	v_cvt_u32_f32_e32 v2, v2
	v_mul_lo_u32 v3, v3, v2
	v_mul_hi_u32 v3, v2, v3
	v_add_u32_e32 v2, v2, v3
	s_waitcnt vmcnt(0) lgkmcnt(0)
	v_mul_hi_u32 v2, v1, v2
	v_mul_lo_u32 v3, v2, v0
	v_sub_u32_e32 v3, v1, v3
	v_cmp_ge_u32_e32 vcc, v3, v0
	v_add_u32_e32 v4, 1, v2
	s_nop 0
	v_cndmask_b32_e32 v2, v2, v4, vcc
	v_sub_u32_e32 v4, v3, v0
	v_cndmask_b32_e32 v3, v3, v4, vcc
	v_cmp_ge_u32_e32 vcc, v3, v0
	v_add_u32_e32 v3, 1, v2
	s_nop 0
	v_cndmask_b32_e32 v2, v2, v3, vcc
	v_add_u32_e32 v3, 1, v1
	v_mad_u64_u32 v[0:1], s[0:1], v0, v2, v[0:1]
	s_add_u32 s0, s36, 0x3500
	s_addc_u32 s1, s37, 0
	v_cmp_ne_u32_e32 vcc, v3, v0
	v_mov_b64_e32 v[0:1], s[0:1]
	s_and_saveexec_b64 s[2:3], vcc
	s_cbranch_execz .LBB0_854
	v_mov_b64_e32 v[0:1], s[0:1]
	flat_load_dword v0, v[0:1] sc1
	s_mov_b64 s[10:11], 0
	s_waitcnt vmcnt(0) lgkmcnt(0)
	v_cmp_eq_u32_e32 vcc, v0, v2
	s_and_saveexec_b64 s[8:9], vcc
	s_cbranch_execz .LBB0_853
	s_add_u32 s6, s36, 0x200
	s_addc_u32 s7, s37, 0
	s_mov_b32 s23, 1
	s_branch .LBB0_846

; __device__ __forceinline__ unsigned xb_ld(unsigned* p)              { return __hip_atomic_load(p, __ATOMIC_RELAXED, __HIP_MEMORY_SCOPE_AGENT); }
; __device__ __forceinline__ unsigned xb_add(unsigned* p, unsigned v) { return __hip_atomic_fetch_add(p, v, __ATOMIC_RELAXED, __HIP_MEMORY_SCOPE_AGENT); }
; #define XB_SPIN(cond, bar) do { unsigned _sp = 0; while (cond) { __builtin_amdgcn_s_sleep(1); \
;     if ((++_sp & 255u) == 0u) { if (xb_ld(&(bar)[XB_TMO])) break; if (_sp > XB_SPIN_CAP) { atomicAdd(&(bar)[XB_TMO], 1u); break; } } } } while (0)
; __device__ __forceinline__ void xcd_barrier(const XcdBarrier& b) {
;     ...
;         if (old + 1u == (gen + 1u) * nloc) {
;             __builtin_amdgcn_fence(__ATOMIC_RELEASE, "agent");
;             asm volatile("s_waitcnt vmcnt(0)" ::: "memory");
;             const unsigned og = xb_add(&bar[XB_TOP], 1u);
;             const unsigned tg = og / nx;
;             if (og + 1u == (tg + 1u) * nx) xb_add(&bar[XB_TOPGEN], 1u);
;             else XB_SPIN(xb_ld(&bar[XB_TOPGEN]) == tg, bar);
.LBB0_1365:
	v_mov_b32_e32 v1, s34
	v_add_co_u32_e32 v2, vcc, 0x3000, v1
	v_mov_b32_e32 v1, s35
	buffer_inv sc1
	buffer_wbl2 sc1
	s_waitcnt vmcnt(0)
	v_addc_co_u32_e32 v3, vcc, 0, v1, vcc
	v_mov_b32_e32 v1, 1
	flat_atomic_add v1, v[2:3], v1 offset:1024 sc0
	v_cvt_f32_u32_e32 v2, v0
	v_sub_u32_e32 v3, 0, v0
	s_mov_b64 s[4:5], -1
	v_rcp_iflag_f32_e32 v2, v2
	s_nop 0
	v_mul_f32_e32 v2, 0x4f7ffffe, v2
	v_cvt_u32_f32_e32 v2, v2
	v_mul_lo_u32 v3, v3, v2
	v_mul_hi_u32 v3, v2, v3
	v_add_u32_e32 v2, v2, v3
	s_waitcnt vmcnt(0) lgkmcnt(0)
	v_mul_hi_u32 v2, v1, v2
	v_mul_lo_u32 v3, v2, v0
	v_sub_u32_e32 v3, v1, v3
	v_cmp_ge_u32_e32 vcc, v3, v0
	v_add_u32_e32 v4, 1, v2
	s_nop 0
	v_cndmask_b32_e32 v2, v2, v4, vcc
	v_sub_u32_e32 v4, v3, v0
	v_cndmask_b32_e32 v3, v3, v4, vcc
	v_cmp_ge_u32_e32 vcc, v3, v0
	v_add_u32_e32 v3, 1, v2
	s_nop 0
	v_cndmask_b32_e32 v2, v2, v3, vcc
	v_add_u32_e32 v3, 1, v1
	v_mad_u64_u32 v[0:1], s[0:1], v0, v2, v[0:1]
	s_add_u32 s0, s34, 0x3500
	s_addc_u32 s1, s35, 0
	v_cmp_ne_u32_e32 vcc, v3, v0
	v_mov_b64_e32 v[0:1], s[0:1]
	s_and_saveexec_b64 s[2:3], vcc
	s_cbranch_execz .LBB0_1377
	v_mov_b64_e32 v[0:1], s[0:1]
	flat_load_dword v0, v[0:1] sc1
	s_mov_b64 s[8:9], 0
	s_waitcnt vmcnt(0) lgkmcnt(0)
	v_cmp_eq_u32_e32 vcc, v0, v2
	s_and_saveexec_b64 s[6:7], vcc
	s_cbranch_execz .LBB0_1376
	s_add_u32 s4, s34, 0x200
	s_addc_u32 s5, s35, 0
	s_mov_b32 s21, 1
	s_branch .LBB0_1369
